# v28 + P7 permlane-swap reduction + attention row-max: drop redundant canonicalising v_max x,x (8 VALU per sub-tile)
# speedup vs baseline: 1.0106x; 1.0106x over previous
; __device__ __forceinline__ float fast_exp2(float x) { return __builtin_amdgcn_exp2f(x); }
; __device__ __forceinline__ void attn_phase(LAS unsigned char* lds, const bf16_t* QKVZ, bf16_t* AO, const float* sink) {
;     ...
;                 for (int qt = 0; qt < 2; ++qt) {
;                     float mx = S[0][qt][0];
; #pragma unroll
;                     for (int kt = 0; kt < 2; ++kt)
; #pragma unroll
;                         for (int i = 0; i < 16; ++i) mx = fmaxf(mx, S[kt][qt][i]);
;                     { const auto rr = __builtin_amdgcn_permlane32_swap(__float_as_uint(mx), __float_as_uint(mx), false, false);
;                       mx = fmaxf(__uint_as_float(rr[0]), __uint_as_float(rr[1])); }
;                     float alpha = 1.0f;
;                     if (!__builtin_expect(__all(mx <= ATT_THR), 1)) {
;                         const float dlt = fmaxf(mx, 0.0f);
;                         alpha = fast_exp2(-dlt); m_[qt] += dlt;
; #pragma unroll
;                         for (int i = 0; i < 16; ++i) { O[0][qt][i] *= alpha; O[1][qt][i] *= alpha; }
; #pragma unroll
;                         for (int kt = 0; kt < 2; ++kt)
; #pragma unroll
;                             for (int i = 0; i < 16; ++i) S[kt][qt][i] -= dlt;
;                     }
.LBB0_314:
	v_max_f32_e32 v6, v128, v129
	v_max3_f32 v6, v6, v130, v131
	v_max3_f32 v6, v6, v132, v133
	v_max3_f32 v6, v6, v134, v135
	v_max3_f32 v6, v6, v136, v137
	v_max3_f32 v6, v6, v138, v139
	v_max3_f32 v6, v6, v140, v141
	v_max3_f32 v6, v6, v142, v143
	v_max3_f32 v6, v6, v96, v97
	v_max3_f32 v6, v6, v98, v99
	v_max3_f32 v6, v6, v100, v101
	v_max3_f32 v6, v6, v102, v103
	v_max3_f32 v6, v6, v104, v105
	v_max3_f32 v6, v6, v106, v107
	v_max3_f32 v6, v6, v108, v109
	v_max3_f32 v6, v6, v110, v111
	v_mov_b32_e32 v8, v6
	s_nop 1
	v_permlane32_swap_b32_e32 v6, v8
	v_max_f32_e32 v8, v6, v8
	v_cmp_ge_f32_e32 vcc, s64, v8
	s_cmp_eq_u64 vcc, exec
	v_mov_b32_e32 v6, 1.0
	s_cbranch_scc0 .LBB0_318
	v_mov_b32_e32 v8, 1.0
.LBB0_316:
	v_max_f32_e32 v12, v112, v113
	v_max3_f32 v12, v12, v114, v115
	v_max3_f32 v12, v12, v116, v117
	v_max3_f32 v12, v12, v118, v119
	v_max3_f32 v12, v12, v120, v121
	v_max3_f32 v12, v12, v122, v123
	v_max3_f32 v12, v12, v124, v125
	v_max3_f32 v12, v12, v126, v127
	v_max3_f32 v12, v12, v80, v81
	v_max3_f32 v12, v12, v82, v83
	v_max3_f32 v12, v12, v84, v85
	v_max3_f32 v12, v12, v86, v87
	v_max3_f32 v12, v12, v88, v89
	v_max3_f32 v12, v12, v90, v91
	v_max3_f32 v12, v12, v92, v93
	v_max3_f32 v12, v12, v94, v95
	v_mov_b32_e32 v13, v12
	s_nop 1
	v_permlane32_swap_b32_e32 v12, v13
	v_max_f32_e32 v12, v12, v13
	v_cmp_ge_f32_e32 vcc, s64, v12
	s_cmp_eq_u64 vcc, exec
	s_cbranch_scc1 .LBB0_309
	v_max_f32_e32 v6, v12, v12
	v_max_f32_e32 v12, 0, v6
	v_exp_f32_e64 v6, -v12
	v_add_f32_e32 v7, v7, v12
	v_pk_add_f32 v[112:113], v[112:113], v[12:13] op_sel_hi:[1,0] neg_lo:[0,1] neg_hi:[0,1]
	v_pk_add_f32 v[114:115], v[114:115], v[12:13] op_sel_hi:[1,0] neg_lo:[0,1] neg_hi:[0,1]
	v_pk_mul_f32 v[46:47], v[46:47], v[6:7] op_sel_hi:[1,0]
	v_pk_mul_f32 v[44:45], v[44:45], v[6:7] op_sel_hi:[1,0]
	v_pk_mul_f32 v[42:43], v[42:43], v[6:7] op_sel_hi:[1,0]
	v_pk_mul_f32 v[40:41], v[40:41], v[6:7] op_sel_hi:[1,0]
	v_pk_mul_f32 v[38:39], v[38:39], v[6:7] op_sel_hi:[1,0]
	v_pk_mul_f32 v[36:37], v[36:37], v[6:7] op_sel_hi:[1,0]
	v_pk_mul_f32 v[34:35], v[34:35], v[6:7] op_sel_hi:[1,0]
	v_pk_mul_f32 v[32:33], v[32:33], v[6:7] op_sel_hi:[1,0]
	v_pk_mul_f32 v[30:31], v[30:31], v[6:7] op_sel_hi:[1,0]
	v_pk_mul_f32 v[28:29], v[28:29], v[6:7] op_sel_hi:[1,0]
	v_pk_mul_f32 v[26:27], v[26:27], v[6:7] op_sel_hi:[1,0]
	v_pk_mul_f32 v[24:25], v[24:25], v[6:7] op_sel_hi:[1,0]
	v_pk_mul_f32 v[22:23], v[22:23], v[6:7] op_sel_hi:[1,0]
	v_pk_mul_f32 v[20:21], v[20:21], v[6:7] op_sel_hi:[1,0]
	v_pk_mul_f32 v[18:19], v[18:19], v[6:7] op_sel_hi:[1,0]
	v_pk_mul_f32 v[16:17], v[16:17], v[6:7] op_sel_hi:[1,0]
	v_pk_add_f32 v[116:117], v[116:117], v[12:13] op_sel_hi:[1,0] neg_lo:[0,1] neg_hi:[0,1]
	v_pk_add_f32 v[118:119], v[118:119], v[12:13] op_sel_hi:[1,0] neg_lo:[0,1] neg_hi:[0,1]
	v_pk_add_f32 v[120:121], v[120:121], v[12:13] op_sel_hi:[1,0] neg_lo:[0,1] neg_hi:[0,1]
	v_pk_add_f32 v[122:123], v[122:123], v[12:13] op_sel_hi:[1,0] neg_lo:[0,1] neg_hi:[0,1]
	v_pk_add_f32 v[124:125], v[124:125], v[12:13] op_sel_hi:[1,0] neg_lo:[0,1] neg_hi:[0,1]
	v_pk_add_f32 v[126:127], v[126:127], v[12:13] op_sel_hi:[1,0] neg_lo:[0,1] neg_hi:[0,1]
	v_pk_add_f32 v[80:81], v[80:81], v[12:13] op_sel_hi:[1,0] neg_lo:[0,1] neg_hi:[0,1]
	v_pk_add_f32 v[82:83], v[82:83], v[12:13] op_sel_hi:[1,0] neg_lo:[0,1] neg_hi:[0,1]
	v_pk_add_f32 v[84:85], v[84:85], v[12:13] op_sel_hi:[1,0] neg_lo:[0,1] neg_hi:[0,1]
	v_pk_add_f32 v[86:87], v[86:87], v[12:13] op_sel_hi:[1,0] neg_lo:[0,1] neg_hi:[0,1]
	v_pk_add_f32 v[88:89], v[88:89], v[12:13] op_sel_hi:[1,0] neg_lo:[0,1] neg_hi:[0,1]
	v_pk_add_f32 v[90:91], v[90:91], v[12:13] op_sel_hi:[1,0] neg_lo:[0,1] neg_hi:[0,1]
	v_pk_add_f32 v[92:93], v[92:93], v[12:13] op_sel_hi:[1,0] neg_lo:[0,1] neg_hi:[0,1]
	v_pk_add_f32 v[94:95], v[94:95], v[12:13] op_sel_hi:[1,0] neg_lo:[0,1] neg_hi:[0,1]
	s_branch .LBB0_309
